# adds conv-phase software pipelining: next 8-row load batch prefetched into spare VGPRs during unpack/FMA of the current batch
# speedup vs baseline: 1.0083x; 1.0083x over previous
; __device__ void conv_phase(LAS unsigned char* lds, const Params& p) {
;     ...
;             const int tok0 = half ? (c0 + line) : (r0 + line) * 64;
;             const unsigned offb = (unsigned)((b * 4096 + tok0) * 512 + ch0) * 2u;
;             asm volatile("" ::: "memory");
;             float cur[2][8];
; #pragma unroll
;             for (int a = 0; a < 2; ++a)
; #pragma unroll
;                 for (int c = 0; c < 8; ++c) cur[a][c] = 0.f;
;             float Wp[8];
; #pragma unroll
;             for (int c = 0; c < 8; ++c) Wp[c] = 0.f;
; #pragma unroll 1
;             for (int hb = 0; hb < 4; ++hb) {
;                 u32x4 raw[8];
; #pragma unroll
;                 for (int q = 0; q < 8; ++q) {
;                     const int xx = base - 15 + hb * 8 + q;
;                     const int xc = min(max(xx, 0), 63);
;                     const u32x4 r = *(const u32x4*)(Pb + (offb + (unsigned)xc * stepB));
;                     const bool ok = (xx == xc);
;                     raw[q] = (u32x4){ok ? r[0] : 0u, ok ? r[1] : 0u, ok ? r[2] : 0u, ok ? r[3] : 0u};
;                 }
.LBB0_373:
	v_or_b32_e32 v3, s10, v124
	v_or_b32_e32 v2, s10, v123
	v_lshlrev_b32_e32 v3, 6, v3
	v_cndmask_b32_e64 v2, v2, v3, s[6:7]
	v_mov_b32_e32 v107, 0
	s_xor_b64 s[38:39], s[8:9], -1
	v_lshl_or_b32 v126, v2, 10, v125
	s_mov_b32 s41, 0
	v_mov_b32_e32 v127, v119
	v_mov_b32_e32 v106, v107
	v_mov_b32_e32 v109, v107
	v_mov_b32_e32 v108, v107
	v_mov_b32_e32 v111, v107
	v_mov_b32_e32 v110, v107
	v_mov_b32_e32 v34, v107
	v_mov_b32_e32 v35, v107
	v_mov_b32_e32 v4, v107
	v_mov_b32_e32 v5, v107
	v_mov_b32_e32 v113, v107
	v_mov_b32_e32 v112, v107
	v_mov_b32_e32 v100, v107
	v_mov_b32_e32 v101, v107
	v_mov_b32_e32 v2, v107
	v_mov_b32_e32 v3, v107
	v_mov_b32_e32 v102, v107
	v_mov_b32_e32 v103, v107
	v_mov_b32_e32 v8, v107
	v_mov_b32_e32 v9, v107
	v_mov_b32_e32 v104, v107
	v_mov_b32_e32 v105, v107
	v_mov_b32_e32 v6, v107
	v_mov_b32_e32 v7, v107
	v_add_u32_e32 v224, s41, v115
	v_add_u32_e32 v225, -15, v224
	v_med3_i32 v226, v225, 0, 63
	v_cmp_eq_u32_e64 s[20:21], v225, v226
	v_lshl_add_u32 v192, v226, v118, v126
	v_add_u32_e32 v225, -14, v224
	v_med3_i32 v226, v225, 0, 63
	v_cmp_eq_u32_e32 vcc, v225, v226
	v_lshl_add_u32 v196, v226, v118, v126
	v_add_u32_e32 v225, -13, v224
	v_med3_i32 v226, v225, 0, 63
	v_cmp_eq_u32_e64 s[8:9], v225, v226
	v_lshl_add_u32 v200, v226, v118, v126
	v_add_u32_e32 v225, -12, v224
	v_med3_i32 v226, v225, 0, 63
	v_cmp_eq_u32_e64 s[10:11], v225, v226
	v_lshl_add_u32 v204, v226, v118, v126
	v_add_u32_e32 v225, -11, v224
	v_med3_i32 v226, v225, 0, 63
	v_cmp_eq_u32_e64 s[12:13], v225, v226
	v_lshl_add_u32 v208, v226, v118, v126
	v_add_u32_e32 v225, -10, v224
	v_med3_i32 v226, v225, 0, 63
	v_cmp_eq_u32_e64 s[14:15], v225, v226
	v_lshl_add_u32 v212, v226, v118, v126
	v_add_u32_e32 v225, -9, v224
	v_med3_i32 v226, v225, 0, 63
	v_cmp_eq_u32_e64 s[16:17], v225, v226
	v_lshl_add_u32 v216, v226, v118, v126
	v_add_u32_e32 v225, -8, v224
	v_med3_i32 v226, v225, 0, 63
	v_cmp_eq_u32_e64 s[18:19], v225, v226
	v_lshl_add_u32 v220, v226, v118, v126
	global_load_dwordx4 v[192:195], v192, s[26:27]
	s_nop 0
	global_load_dwordx4 v[196:199], v196, s[26:27]
	s_nop 0
	global_load_dwordx4 v[200:203], v200, s[26:27]
	s_nop 0
	global_load_dwordx4 v[204:207], v204, s[26:27]
	s_nop 0
	global_load_dwordx4 v[208:211], v208, s[26:27]
	s_nop 0
	global_load_dwordx4 v[212:215], v212, s[26:27]
	s_nop 0
	global_load_dwordx4 v[216:219], v216, s[26:27]
	s_nop 0
	global_load_dwordx4 v[220:223], v220, s[26:27]
.LBB0_374:
	ds_read_b128 v[14:17], v127
	ds_read_b128 v[10:13], v127 offset:16
	v_mov_b32_e32 v116, v35
	v_mov_b32_e32 v117, v34
	ds_read_b128 v[22:25], v127 offset:2048
	ds_read_b128 v[18:21], v127 offset:2064
	ds_read_b128 v[30:33], v127 offset:4096
	ds_read_b128 v[26:29], v127 offset:4112
	ds_read_b128 v[38:41], v127 offset:6144
	ds_read_b128 v[34:37], v127 offset:6160
	ds_read_b128 v[46:49], v127 offset:8192
	ds_read_b128 v[42:45], v127 offset:8208
	ds_read_b128 v[54:57], v127 offset:10240
	ds_read_b128 v[50:53], v127 offset:10256
	ds_read_b128 v[62:65], v127 offset:12288
	ds_read_b128 v[58:61], v127 offset:12304
	s_waitcnt vmcnt(7)
	v_cndmask_b32_e64 v160, 0, v192, s[20:21]
	v_cndmask_b32_e64 v161, 0, v193, s[20:21]
	v_cndmask_b32_e64 v162, 0, v194, s[20:21]
	v_cndmask_b32_e64 v163, 0, v195, s[20:21]
	s_waitcnt vmcnt(6)
	v_cndmask_b32_e32 v164, 0, v196, vcc
	v_cndmask_b32_e32 v165, 0, v197, vcc
	v_cndmask_b32_e32 v166, 0, v198, vcc
	v_cndmask_b32_e32 v167, 0, v199, vcc
	s_waitcnt vmcnt(5)
	v_cndmask_b32_e64 v168, 0, v200, s[8:9]
	v_cndmask_b32_e64 v169, 0, v201, s[8:9]
	v_cndmask_b32_e64 v170, 0, v202, s[8:9]
	v_cndmask_b32_e64 v171, 0, v203, s[8:9]
	s_waitcnt vmcnt(4)
	v_cndmask_b32_e64 v172, 0, v204, s[10:11]
	v_cndmask_b32_e64 v173, 0, v205, s[10:11]
	v_cndmask_b32_e64 v174, 0, v206, s[10:11]
	v_cndmask_b32_e64 v175, 0, v207, s[10:11]
	s_waitcnt vmcnt(3)
	v_cndmask_b32_e64 v176, 0, v208, s[12:13]
	v_cndmask_b32_e64 v177, 0, v209, s[12:13]
	v_cndmask_b32_e64 v178, 0, v210, s[12:13]
	v_cndmask_b32_e64 v179, 0, v211, s[12:13]
	s_waitcnt vmcnt(2)
	v_cndmask_b32_e64 v180, 0, v212, s[14:15]
	v_cndmask_b32_e64 v181, 0, v213, s[14:15]
	v_cndmask_b32_e64 v182, 0, v214, s[14:15]
	v_cndmask_b32_e64 v183, 0, v215, s[14:15]
	s_waitcnt vmcnt(1)
	v_cndmask_b32_e64 v184, 0, v216, s[16:17]
	v_cndmask_b32_e64 v185, 0, v217, s[16:17]
	v_cndmask_b32_e64 v186, 0, v218, s[16:17]
	v_cndmask_b32_e64 v187, 0, v219, s[16:17]
	s_waitcnt vmcnt(0)
	v_cndmask_b32_e64 v188, 0, v220, s[18:19]
	v_cndmask_b32_e64 v189, 0, v221, s[18:19]
	v_cndmask_b32_e64 v190, 0, v222, s[18:19]
	v_cndmask_b32_e64 v191, 0, v223, s[18:19]
	s_add_i32 s41, s41, 8
	s_cmp_eq_u32 s41, 32
	s_cbranch_scc1 .Lp4_nopf
	v_add_u32_e32 v224, s41, v115
	v_add_u32_e32 v225, -15, v224
	v_med3_i32 v226, v225, 0, 63
	v_cmp_eq_u32_e64 s[20:21], v225, v226
	v_lshl_add_u32 v192, v226, v118, v126
	v_add_u32_e32 v225, -14, v224
	v_med3_i32 v226, v225, 0, 63
	v_cmp_eq_u32_e32 vcc, v225, v226
	v_lshl_add_u32 v196, v226, v118, v126
	v_add_u32_e32 v225, -13, v224
	v_med3_i32 v226, v225, 0, 63
	v_cmp_eq_u32_e64 s[8:9], v225, v226
	v_lshl_add_u32 v200, v226, v118, v126
	v_add_u32_e32 v225, -12, v224
	v_med3_i32 v226, v225, 0, 63
	v_cmp_eq_u32_e64 s[10:11], v225, v226
	v_lshl_add_u32 v204, v226, v118, v126
	v_add_u32_e32 v225, -11, v224
	v_med3_i32 v226, v225, 0, 63
	v_cmp_eq_u32_e64 s[12:13], v225, v226
	v_lshl_add_u32 v208, v226, v118, v126
	v_add_u32_e32 v225, -10, v224
	v_med3_i32 v226, v225, 0, 63
	v_cmp_eq_u32_e64 s[14:15], v225, v226
	v_lshl_add_u32 v212, v226, v118, v126
	v_add_u32_e32 v225, -9, v224
	v_med3_i32 v226, v225, 0, 63
	v_cmp_eq_u32_e64 s[16:17], v225, v226
	v_lshl_add_u32 v216, v226, v118, v126
	v_add_u32_e32 v225, -8, v224
	v_med3_i32 v226, v225, 0, 63
	v_cmp_eq_u32_e64 s[18:19], v225, v226
	v_lshl_add_u32 v220, v226, v118, v126
	global_load_dwordx4 v[192:195], v192, s[26:27]
	s_nop 0
	global_load_dwordx4 v[196:199], v196, s[26:27]
	s_nop 0
	global_load_dwordx4 v[200:203], v200, s[26:27]
	s_nop 0
	global_load_dwordx4 v[204:207], v204, s[26:27]
	s_nop 0
	global_load_dwordx4 v[208:211], v208, s[26:27]
	s_nop 0
	global_load_dwordx4 v[212:215], v212, s[26:27]
	s_nop 0
	global_load_dwordx4 v[216:219], v216, s[26:27]
	s_nop 0
	global_load_dwordx4 v[220:223], v220, s[26:27]
; #define LAS __attribute__((address_space(3)))
; __device__ __forceinline__ float bf_lo(unsigned u) { return __uint_as_float(u << 16); }
; __device__ __forceinline__ float bf_hi(unsigned u) { return __uint_as_float(u & 0xffff0000u); }
; __device__ void conv_phase(LAS unsigned char* lds, const Params& p) {
;     ...
;                 for (int q = 0; q < 8; ++q) {
;                     const int xx = base - 15 + hb * 8 + q;
;                     const int xc = min(max(xx, 0), 63);
;                     const u32x4 r = *(const u32x4*)(Pb + (offb + (unsigned)xc * stepB));
;                     const bool ok = (xx == xc);
;                     raw[q] = (u32x4){ok ? r[0] : 0u, ok ? r[1] : 0u, ok ? r[2] : 0u, ok ? r[3] : 0u};
;                 }
;                 const LAS float* wrow = wl + hb * 8 * 512 + ch0;
; #pragma unroll
;                 for (int q = 0; q < 8; ++q) {
;                     const float in[8] = {bf_lo(raw[q][0]), bf_hi(raw[q][0]), bf_lo(raw[q][1]), bf_hi(raw[q][1]), bf_lo(raw[q][2]), bf_hi(raw[q][2]), bf_lo(raw[q][3]), bf_hi(raw[q][3])};
;                     const f32x4 wa = *(const LAS f32x4*)(wrow + q * 512), wb = *(const LAS f32x4*)(wrow + q * 512 + 4);
;                     const float Wc[8] = {wa[0], wa[1], wa[2], wa[3], wb[0], wb[1], wb[2], wb[3]};
; #pragma unroll
;                     for (int c = 0; c < 8; ++c) { cur[0][c] += Wc[c] * in[c]; cur[1][c] += Wp[c] * in[c]; Wp[c] = Wc[c]; }
;                 }
;             }
; #pragma unroll
;             for (int j = 0; j < 2; ++j)
; #pragma unroll
;                 for (int c = 0; c < 8; ++c) { if (line == 0) acc[j][c] = cur[j][c]; else acc[2 + j][c] = cur[j][c]; }
.Lp4_nopf:
	v_lshlrev_b32_e32 v128, 16, v160
	v_and_b32_e32 v129, 0xffff0000, v160
	v_lshlrev_b32_e32 v130, 16, v161
	v_and_b32_e32 v131, 0xffff0000, v161
	v_lshlrev_b32_e32 v132, 16, v162
	v_and_b32_e32 v133, 0xffff0000, v162
	v_lshlrev_b32_e32 v134, 16, v163
	v_and_b32_e32 v135, 0xffff0000, v163
	v_lshlrev_b32_e32 v136, 16, v164
	v_and_b32_e32 v137, 0xffff0000, v164
	v_lshlrev_b32_e32 v138, 16, v165
	v_and_b32_e32 v139, 0xffff0000, v165
	v_lshlrev_b32_e32 v140, 16, v166
	v_and_b32_e32 v141, 0xffff0000, v166
	v_lshlrev_b32_e32 v142, 16, v167
	v_and_b32_e32 v143, 0xffff0000, v167
	v_pk_fma_f32 v[104:105], v[6:7], v[128:129], v[104:105]
	v_pk_fma_f32 v[102:103], v[8:9], v[130:131], v[102:103]
	v_pk_fma_f32 v[100:101], v[2:3], v[132:133], v[100:101]
	v_pk_fma_f32 v[116:117], v[4:5], v[134:135], v[116:117]
	s_waitcnt lgkmcnt(12)
	v_pk_fma_f32 v[112:113], v[12:13], v[134:135], v[112:113]
	v_pk_fma_f32 v[110:111], v[14:15], v[128:129], v[110:111]
	v_pk_fma_f32 v[108:109], v[16:17], v[130:131], v[108:109]
	v_pk_fma_f32 v[106:107], v[10:11], v[132:133], v[106:107]
	v_lshlrev_b32_e32 v144, 16, v168
	v_and_b32_e32 v145, 0xffff0000, v168
	v_lshlrev_b32_e32 v146, 16, v169
	v_and_b32_e32 v147, 0xffff0000, v169
	v_lshlrev_b32_e32 v148, 16, v170
	v_and_b32_e32 v149, 0xffff0000, v170
	v_lshlrev_b32_e32 v150, 16, v171
	v_and_b32_e32 v151, 0xffff0000, v171
	v_pk_fma_f32 v[12:13], v[12:13], v[142:143], v[116:117]
	s_waitcnt lgkmcnt(10)
	v_pk_fma_f32 v[112:113], v[20:21], v[142:143], v[112:113]
	v_pk_fma_f32 v[110:111], v[22:23], v[136:137], v[110:111]
	v_pk_fma_f32 v[14:15], v[14:15], v[136:137], v[104:105]
	v_pk_fma_f32 v[104:105], v[24:25], v[138:139], v[108:109]
	v_pk_fma_f32 v[16:17], v[16:17], v[138:139], v[102:103]
	v_pk_fma_f32 v[102:103], v[18:19], v[140:141], v[106:107]
	v_pk_fma_f32 v[10:11], v[10:11], v[140:141], v[100:101]
	v_lshlrev_b32_e32 v152, 16, v172
	v_and_b32_e32 v153, 0xffff0000, v172
	v_lshlrev_b32_e32 v154, 16, v173
	v_and_b32_e32 v155, 0xffff0000, v173
	v_lshlrev_b32_e32 v156, 16, v174
	v_and_b32_e32 v157, 0xffff0000, v174
	v_lshlrev_b32_e32 v158, 16, v175
	v_and_b32_e32 v159, 0xffff0000, v175
	ds_read_b128 v[6:9], v127 offset:14336
	ds_read_b128 v[2:5], v127 offset:14352
	v_pk_fma_f32 v[12:13], v[20:21], v[150:151], v[12:13]
	s_waitcnt lgkmcnt(10)
	v_pk_fma_f32 v[20:21], v[28:29], v[150:151], v[112:113]
	v_pk_fma_f32 v[100:101], v[30:31], v[144:145], v[110:111]
	v_pk_fma_f32 v[14:15], v[22:23], v[144:145], v[14:15]
	v_pk_fma_f32 v[22:23], v[32:33], v[146:147], v[104:105]
	v_pk_fma_f32 v[16:17], v[24:25], v[146:147], v[16:17]
	v_pk_fma_f32 v[24:25], v[26:27], v[148:149], v[102:103]
	v_pk_fma_f32 v[10:11], v[18:19], v[148:149], v[10:11]
	v_lshlrev_b32_e32 v160, 16, v176
	v_and_b32_e32 v161, 0xffff0000, v176
	v_lshlrev_b32_e32 v162, 16, v177
	v_and_b32_e32 v163, 0xffff0000, v177
	v_lshlrev_b32_e32 v164, 16, v178
	v_and_b32_e32 v165, 0xffff0000, v178
	v_lshlrev_b32_e32 v166, 16, v179
	v_and_b32_e32 v167, 0xffff0000, v179
	v_pk_fma_f32 v[12:13], v[28:29], v[158:159], v[12:13]
	s_waitcnt lgkmcnt(8)
	v_pk_fma_f32 v[18:19], v[36:37], v[158:159], v[20:21]
	v_pk_fma_f32 v[20:21], v[38:39], v[152:153], v[100:101]
	v_pk_fma_f32 v[14:15], v[30:31], v[152:153], v[14:15]
	v_pk_fma_f32 v[22:23], v[40:41], v[154:155], v[22:23]
	v_pk_fma_f32 v[16:17], v[32:33], v[154:155], v[16:17]
	v_pk_fma_f32 v[24:25], v[34:35], v[156:157], v[24:25]
	v_pk_fma_f32 v[10:11], v[26:27], v[156:157], v[10:11]
	v_lshlrev_b32_e32 v168, 16, v180
	v_and_b32_e32 v169, 0xffff0000, v180
	v_lshlrev_b32_e32 v170, 16, v181
	v_and_b32_e32 v171, 0xffff0000, v181
	v_lshlrev_b32_e32 v172, 16, v182
	v_and_b32_e32 v173, 0xffff0000, v182
	v_lshlrev_b32_e32 v174, 16, v183
	v_and_b32_e32 v175, 0xffff0000, v183
	v_pk_fma_f32 v[12:13], v[36:37], v[166:167], v[12:13]
	s_waitcnt lgkmcnt(6)
	v_pk_fma_f32 v[18:19], v[44:45], v[166:167], v[18:19]
	v_pk_fma_f32 v[20:21], v[46:47], v[160:161], v[20:21]
	v_pk_fma_f32 v[14:15], v[38:39], v[160:161], v[14:15]
	v_pk_fma_f32 v[22:23], v[48:49], v[162:163], v[22:23]
	v_pk_fma_f32 v[16:17], v[40:41], v[162:163], v[16:17]
	v_pk_fma_f32 v[24:25], v[42:43], v[164:165], v[24:25]
	v_pk_fma_f32 v[10:11], v[34:35], v[164:165], v[10:11]
	v_lshlrev_b32_e32 v176, 16, v184
	v_and_b32_e32 v177, 0xffff0000, v184
	v_lshlrev_b32_e32 v178, 16, v185
	v_and_b32_e32 v179, 0xffff0000, v185
	v_lshlrev_b32_e32 v180, 16, v186
	v_and_b32_e32 v181, 0xffff0000, v186
	v_lshlrev_b32_e32 v183, 16, v187
	v_and_b32_e32 v182, 0xffff0000, v187
	v_lshlrev_b32_e32 v184, 16, v188
	v_and_b32_e32 v185, 0xffff0000, v188
	v_lshlrev_b32_e32 v186, 16, v189
	v_and_b32_e32 v187, 0xffff0000, v189
	v_lshlrev_b32_e32 v188, 16, v190
	v_and_b32_e32 v189, 0xffff0000, v190
	v_lshlrev_b32_e32 v190, 16, v191
	v_and_b32_e32 v191, 0xffff0000, v191
	v_pk_fma_f32 v[12:13], v[44:45], v[174:175], v[12:13]
	s_waitcnt lgkmcnt(4)
	v_pk_fma_f32 v[18:19], v[52:53], v[174:175], v[18:19]
	v_pk_fma_f32 v[20:21], v[54:55], v[168:169], v[20:21]
	v_pk_fma_f32 v[14:15], v[46:47], v[168:169], v[14:15]
	v_pk_fma_f32 v[22:23], v[56:57], v[170:171], v[22:23]
	v_pk_fma_f32 v[16:17], v[48:49], v[170:171], v[16:17]
	v_pk_fma_f32 v[24:25], v[50:51], v[172:173], v[24:25]
	v_pk_fma_f32 v[10:11], v[42:43], v[172:173], v[10:11]
	s_waitcnt lgkmcnt(2)
	v_pk_mul_f32 v[128:129], v[60:61], v[190:191]
	v_pk_fma_f32 v[18:19], v[60:61], v[182:183], v[18:19] op_sel:[0,1,0] op_sel_hi:[1,0,1]
	v_pk_fma_f32 v[20:21], v[62:63], v[176:177], v[20:21]
	v_pk_fma_f32 v[14:15], v[54:55], v[176:177], v[14:15]
	v_pk_fma_f32 v[22:23], v[64:65], v[178:179], v[22:23]
	v_pk_fma_f32 v[16:17], v[56:57], v[178:179], v[16:17]
	v_pk_fma_f32 v[24:25], v[58:59], v[180:181], v[24:25]
	v_pk_fma_f32 v[10:11], v[50:51], v[180:181], v[10:11]
	v_pk_fma_f32 v[12:13], v[52:53], v[182:183], v[12:13] op_sel:[1,0,1] op_sel_hi:[0,1,0]
	v_add_u32_e32 v127, 0x4000, v127
	s_waitcnt lgkmcnt(1)
	v_pk_fma_f32 v[110:111], v[6:7], v[184:185], v[20:21]
	v_pk_fma_f32 v[104:105], v[62:63], v[184:185], v[14:15]
	v_pk_fma_f32 v[108:109], v[8:9], v[186:187], v[22:23]
	v_pk_fma_f32 v[102:103], v[64:65], v[186:187], v[16:17]
	s_waitcnt lgkmcnt(0)
	v_pk_fma_f32 v[106:107], v[2:3], v[188:189], v[24:25]
	v_pk_fma_f32 v[100:101], v[58:59], v[188:189], v[10:11]
	v_pk_fma_f32 v[112:113], v[4:5], v[190:191], v[18:19]
	v_pk_add_f32 v[34:35], v[12:13], v[128:129] op_sel:[0,1] op_sel_hi:[1,0]
	s_cmp_eq_u32 s41, 32
	s_cbranch_scc0 .LBB0_374
	s_mov_b32 s10, 1
	s_mov_b64 s[8:9], 0
	s_and_b64 vcc, exec, s[38:39]
	s_cbranch_vccnz .LBB0_371
	v_mov_b32_e32 v121, v34
	v_mov_b32_e32 v122, v35
	v_mov_b64_e32 v[86:87], v[106:107]
	v_mov_b64_e32 v[90:91], v[108:109]
	v_mov_b64_e32 v[92:93], v[110:111]
	v_mov_b64_e32 v[94:95], v[100:101]
	v_mov_b64_e32 v[96:97], v[102:103]
	v_mov_b64_e32 v[98:99], v[104:105]
	v_mov_b32_e32 v88, v113
	v_mov_b32_e32 v89, v112
	s_branch .LBB0_373
